# w_in phase round 2: 170 idle workgroups run 170 plain (no V^T) attention-side w_in units taken from the mixer queue; queue keeps V^T units + 86 plain
# speedup vs baseline: 1.0107x; 1.0107x over previous
.Lwsteal:
	s_cmp_lg_u32 s25, 0
	s_cbranch_scc1 .LBB0_236
	s_add_i32 s5, s24, 0xfffffeaa
	s_cmpk_lt_u32 s5, 0xaa
	s_cbranch_scc0 .LBB0_236
	s_add_i32 s5, s5, 0x56
	s_lshr_b32 s20, s5, 2
	s_and_b32 s21, s5, 3
	s_min_u32 s5, s21, 1
	s_add_i32 s21, s21, s5
	s_add_i32 s5, s21, 5
	s_cmp_lt_u32 s21, 4
	s_cselect_b32 s22, s21, s5
	s_mov_b64 s[2:3], -1

.LBB0_834:
	s_andn2_b64 vcc, exec, s[2:3]
	s_cbranch_vccnz .LBB0_666
	s_waitcnt vmcnt(0)
	v_mov_b32_e32 v13, v156
	s_cmpk_lt_u32 s43, 0x80
	s_cbranch_scc0 .Lq_plain
	s_lshr_b32 s2, s43, 1
	s_mul_i32 s2, s2, 6
	s_and_b32 s3, s43, 1
	s_lshl_b32 s3, s3, 2
	s_add_i32 s2, s2, s3
	s_add_i32 s43, s2, 1
	s_branch .Lq_done
.Lq_plain:
	s_add_i32 s3, s43, 0xffffff80
	s_lshr_b32 s2, s3, 2
	s_mul_i32 s2, s2, 6
	s_and_b32 s3, s3, 3
	s_add_i32 s2, s2, s3
	s_min_u32 s3, s3, 1
	s_add_i32 s43, s2, s3
.Lq_done:
	s_mul_hi_i32 s2, s43, 0x2aaaaaab
	v_lshlrev_b32_e32 v0, 4, v13
	v_add_u32_e32 v2, 0x2000, v0
	v_ashrrev_i32_e32 v3, 31, v2
	v_lshrrev_b32_e32 v3, 22, v3
	v_add_u32_e32 v3, v2, v3
	v_ashrrev_i32_e32 v10, 10, v3
	v_mul_i32_i24_e32 v3, 0x400, v10
	v_sub_u32_e32 v2, v2, v3
	v_lshrrev_b32_e32 v3, 4, v2
	s_lshr_b32 s3, s2, 31
	v_bitop3_b32 v2, v3, v2, 32 bitop3:0x6c
	s_add_i32 s2, s2, s3
	v_ashrrev_i32_e32 v3, 31, v2
	s_mul_i32 s3, s2, -6
	v_lshrrev_b32_e32 v3, 26, v3
	s_add_i32 s3, s3, s43
	v_add_u32_e32 v3, v2, v3
	v_lshlrev_b32_e32 v4, 3, v10
	s_add_i32 s4, s3, 5
	v_ashrrev_i32_e32 v11, 6, v3
	v_and_b32_e32 v4, -16, v4
	s_cmp_lt_i32 s3, 4
	v_add_u32_e32 v4, v11, v4
	s_cselect_b32 s4, s3, s4
	v_and_b32_e32 v5, 3, v11
	s_mov_b32 s3, 0x1fffe0
	v_lshrrev_b32_e32 v6, 2, v4
	v_lshlrev_b32_e32 v7, 1, v4
	v_and_b32_e32 v3, 0xc0, v3
	v_and_or_b32 v5, v4, s3, v5
	v_and_b32_e32 v6, 4, v6
	v_and_b32_e32 v7, 24, v7
	v_sub_u32_e32 v2, v2, v3
	v_or3_b32 v5, v5, v6, v7
	v_lshlrev_b32_e32 v6, 5, v10
	v_ashrrev_i16_sdwa v2, v167, sext(v2) dst_sel:DWORD dst_unused:UNUSED_PAD src0_sel:DWORD src1_sel:BYTE_0
	v_and_b32_e32 v6, 32, v6
	v_bfe_i32 v12, v2, 0, 16
	v_add_lshl_u32 v2, v6, v12, 1
	v_lshl_add_u32 v134, v5, 11, v2
	v_lshl_add_u32 v136, v4, 11, v2
	v_bfe_i32 v2, v13, 27, 1
	v_lshrrev_b32_e32 v2, 22, v2
	v_add_u32_e32 v2, v0, v2
	v_and_b32_e32 v2, 0xfffffc00, v2
	v_sub_u32_e32 v0, v0, v2
	v_lshrrev_b32_e32 v2, 4, v0
	v_bitop3_b32 v2, v2, v0, 32 bitop3:0x6c
	v_ashrrev_i32_e32 v0, 31, v0
	v_lshrrev_b32_e32 v0, 26, v0
	v_add_u32_e32 v0, v2, v0
	v_ashrrev_i32_e32 v14, 6, v0
	v_ashrrev_i32_e32 v0, 31, v13
	v_lshrrev_b32_e32 v0, 26, v0
	v_add_u32_e32 v0, v13, v0
	v_ashrrev_i32_e32 v15, 6, v0
	v_lshlrev_b32_e32 v0, 3, v15
	v_and_b32_e32 v0, -16, v0
	v_add_u32_e32 v3, v14, v0
	v_and_b32_e32 v0, 3, v14
	v_lshrrev_b32_e32 v4, 2, v3
	v_lshlrev_b32_e32 v5, 1, v3
	v_and_or_b32 v0, v3, s3, v0
	v_and_b32_e32 v4, 4, v4
	v_and_b32_e32 v5, 24, v5
	v_readfirstlane_b32 s34, v13
	v_or3_b32 v0, v0, v4, v5
	v_mul_i32_i24_e32 v5, 64, v14
	s_ashr_i32 s14, s34, 6
	v_sub_u32_e32 v2, v2, v5
	s_ashr_i32 s3, s2, 31
	s_ashr_i32 s5, s4, 31
	s_ashr_i32 s15, s34, 8
	s_lshl_b32 s35, s14, 10
	v_lshlrev_b32_e32 v4, 5, v15
	v_ashrrev_i16_sdwa v2, v167, sext(v2) dst_sel:DWORD dst_unused:UNUSED_PAD src0_sel:DWORD src1_sel:BYTE_0
	s_lshl_b64 s[12:13], s[2:3], 19
	s_lshl_b64 s[10:11], s[4:5], 19
	v_and_b32_e32 v4, 32, v4
	v_bfe_i32 v16, v2, 0, 16
	s_add_u32 s6, s92, s10
	v_add_lshl_u32 v2, v4, v16, 1
	s_addc_u32 s7, s96, s11
	s_add_i32 s3, s35, 0
	v_lshl_add_u32 v0, v0, 11, v2
	s_add_i32 m0, s3, 0x10000
	v_lshl_add_u32 v138, v3, 11, v2
	global_load_lds_dwordx4 v0, s[6:7]
	s_add_i32 m0, s3, 0x12000
	s_add_u32 s8, s6, 0x40000
	global_load_lds_dwordx4 v134, s[6:7]
	s_addc_u32 s9, s7, 0
	s_add_i32 m0, s3, 0x14000
	v_mov_b32_e32 v135, v1
	global_load_lds_dwordx4 v0, s[8:9]
	s_add_i32 m0, s3, 0x16000
	v_mov_b32_e32 v139, v1
	global_load_lds_dwordx4 v134, s[8:9]
	s_add_u32 s8, s86, s12
	s_addc_u32 s9, s87, s13
	s_add_i32 s5, s3, 0x2000
	s_mov_b32 m0, s3
	s_add_u32 s52, s8, 0x40000
	global_load_lds_dwordx4 v138, s[8:9]
	s_mov_b32 m0, s5
	s_addc_u32 s53, s9, 0
	s_add_i32 s43, s3, 0x4000
	global_load_lds_dwordx4 v136, s[8:9]
	s_mov_b32 m0, s43
	s_add_i32 s44, s3, 0x6000
	global_load_lds_dwordx4 v138, s[52:53]
	s_mov_b32 m0, s44
	v_mov_b32_e32 v137, v1
	global_load_lds_dwordx4 v136, s[52:53]
	v_lshl_add_u64 v[8:9], s[6:7], 0, v[0:1]
	v_lshl_add_u64 v[6:7], s[6:7], 0, v[134:135]
	v_lshl_add_u64 v[4:5], s[8:9], 0, v[138:139]
	s_cmp_lg_u32 s15, 1
	v_lshl_add_u64 v[2:3], s[8:9], 0, v[136:137]
	s_cbranch_scc1 .LBB0_837
	s_barrier
